# FFN2-down final epilogue: the 8 row-group sum-of-squares slot reads batched up front (dwordx4 sc1), each round tests its prefetched copy before falling back to the polling loop
# baseline (speedup 1.0000x reference)
.LBB0_990:
	s_or_b64 exec, exec, s[22:23]
	v_lshl_add_u64 v[4:5], v[146:147], 2, s[16:17]
	global_load_dwordx4 v[8:11], v[4:5], off offset:16
	global_load_dwordx4 v[12:15], v[4:5], off
	s_waitcnt lgkmcnt(0)
	global_load_dwordx4 v[0:3], v[4:5], off offset:528
	s_nop 0
	global_load_dwordx4 v[4:7], v[4:5], off offset:512
	v_lshl_add_u64 v[212:213], v[136:137], 0, v[182:183]
	global_load_dwordx4 v[212:215], v[212:213], off sc1
	v_lshl_add_u64 v[216:217], v[136:137], 0, v[180:181]
	global_load_dwordx4 v[216:219], v[216:217], off sc1
	v_lshl_add_u64 v[220:221], v[136:137], 0, v[184:185]
	global_load_dwordx4 v[220:223], v[220:221], off sc1
	v_lshl_add_u64 v[224:225], v[136:137], 0, v[186:187]
	global_load_dwordx4 v[224:227], v[224:225], off sc1
	v_lshl_add_u64 v[228:229], v[136:137], 0, v[188:189]
	global_load_dwordx4 v[228:231], v[228:229], off sc1
	v_lshl_add_u64 v[232:233], v[136:137], 0, v[190:191]
	global_load_dwordx4 v[232:235], v[232:233], off sc1
	v_lshl_add_u64 v[236:237], v[136:137], 0, v[192:193]
	global_load_dwordx4 v[236:239], v[236:237], off sc1
	v_lshl_add_u64 v[244:245], v[136:137], 0, v[194:195]
	global_load_dwordx4 v[244:247], v[244:245], off sc1
	v_lshl_add_u64 v[198:199], v[136:137], 0, v[182:183]
	s_mov_b32 s10, 0
	s_waitcnt vmcnt(7)
	v_mov_b32_e32 v182, v212
	v_mov_b32_e32 v196, v213
	v_mov_b32_e32 v183, v214
	v_mov_b32_e32 v197, v215
	v_min3_f32 v210, v182, v196, v183
	v_max_f32_e32 v211, v197, v197
	v_min_f32_e32 v210, v210, v211
	v_cmp_gt_f32_e32 vcc, 0, v210
	s_cbranch_vccz .LBB0_996
	s_branch .LBB0_993

.LBB0_996:
	v_pk_add_f32 v[182:183], v[182:183], v[196:197]
	v_lshlrev_b64 v[148:149], 12, v[148:149]
	v_add_f32_e32 v182, v182, v183
	ds_bpermute_b32 v183, v208, v182
	v_lshl_add_u64 v[148:149], s[8:9], 0, v[148:149]
	s_waitcnt lgkmcnt(0)
	v_add_f32_e32 v182, v182, v183
	ds_bpermute_b32 v183, v209, v182
	s_waitcnt lgkmcnt(0)
	v_add_f32_e32 v182, v182, v183
	v_fmamk_f32 v182, v182, 0x3a800000, v207
	v_mul_f32_e32 v183, 0x4b800000, v182
	v_cmp_gt_f32_e32 vcc, s49, v182
	s_nop 1
	v_cndmask_b32_e32 v182, v182, v183, vcc
	v_rsq_f32_e32 v196, v182
	v_lshl_add_u64 v[182:183], v[146:147], 2, v[148:149]
	v_mul_f32_e32 v148, 0x45800000, v196
	v_cndmask_b32_e32 v196, v196, v148, vcc
	v_pk_mul_f32 v[148:149], v[150:151], v[196:197] op_sel_hi:[1,0]
	v_pk_mul_f32 v[126:127], v[126:127], v[196:197] op_sel_hi:[1,0]
	v_pk_mul_f32 v[198:199], v[124:125], v[196:197] op_sel_hi:[1,0]
	v_pk_mul_f32 v[150:151], v[122:123], v[196:197] op_sel_hi:[1,0]
	v_pk_mul_f32 v[124:125], v[14:15], v[126:127]
	v_pk_mul_f32 v[122:123], v[12:13], v[148:149]
	v_pk_mul_f32 v[150:151], v[10:11], v[150:151]
	v_pk_mul_f32 v[148:149], v[8:9], v[198:199]
	global_store_dwordx4 v[182:183], v[122:125], off nt
	global_store_dwordx4 v[182:183], v[148:151], off offset:16 nt
	v_pk_mul_f32 v[118:119], v[118:119], v[196:197] op_sel_hi:[1,0]
	v_pk_mul_f32 v[122:123], v[120:121], v[196:197] op_sel_hi:[1,0]
	v_pk_mul_f32 v[120:121], v[6:7], v[118:119]
	v_pk_mul_f32 v[118:119], v[4:5], v[122:123]
	global_store_dwordx4 v[182:183], v[118:121], off offset:512 nt
	v_pk_mul_f32 v[114:115], v[114:115], v[196:197] op_sel_hi:[1,0]
	s_nop 0
	v_pk_mul_f32 v[118:119], v[116:117], v[196:197] op_sel_hi:[1,0]
	v_pk_mul_f32 v[116:117], v[2:3], v[114:115]
	v_pk_mul_f32 v[114:115], v[0:1], v[118:119]
	global_store_dwordx4 v[182:183], v[114:117], off offset:528 nt
	s_nop 1
	v_lshl_add_u64 v[114:115], v[136:137], 0, v[180:181]
	s_waitcnt vmcnt(10)
	v_mov_b32_e32 v116, v216
	v_mov_b32_e32 v118, v217
	v_mov_b32_e32 v117, v218
	v_mov_b32_e32 v119, v219
	v_min3_f32 v120, v116, v118, v117
	v_max_f32_e32 v121, v119, v119
	v_min_f32_e32 v120, v120, v121
	v_cmp_gt_f32_e32 vcc, 0, v120
	s_cbranch_vccz .LBB0_1002
	s_branch .LBB0_999

.LBB0_1002:
	v_pk_add_f32 v[114:115], v[116:117], v[118:119]
	v_lshlrev_b64 v[112:113], 12, v[112:113]
	v_add_f32_e32 v114, v114, v115
	ds_bpermute_b32 v115, v208, v114
	v_lshl_add_u64 v[112:113], s[8:9], 0, v[112:113]
	s_waitcnt lgkmcnt(0)
	v_add_f32_e32 v114, v114, v115
	ds_bpermute_b32 v115, v209, v114
	s_waitcnt lgkmcnt(0)
	v_add_f32_e32 v114, v114, v115
	v_fmamk_f32 v114, v114, 0x3a800000, v207
	v_mul_f32_e32 v115, 0x4b800000, v114
	v_cmp_gt_f32_e32 vcc, s49, v114
	s_nop 1
	v_cndmask_b32_e32 v114, v114, v115, vcc
	v_rsq_f32_e32 v116, v114
	v_lshl_add_u64 v[114:115], v[146:147], 2, v[112:113]
	v_mul_f32_e32 v112, 0x45800000, v116
	v_cndmask_b32_e32 v116, v116, v112, vcc
	v_pk_mul_f32 v[112:113], v[152:153], v[116:117] op_sel_hi:[1,0]
	v_pk_mul_f32 v[110:111], v[110:111], v[116:117] op_sel_hi:[1,0]
	v_pk_mul_f32 v[118:119], v[108:109], v[116:117] op_sel_hi:[1,0]
	v_pk_mul_f32 v[120:121], v[106:107], v[116:117] op_sel_hi:[1,0]
	v_pk_mul_f32 v[108:109], v[14:15], v[110:111]
	v_pk_mul_f32 v[106:107], v[12:13], v[112:113]
	v_pk_mul_f32 v[112:113], v[10:11], v[120:121]
	v_pk_mul_f32 v[110:111], v[8:9], v[118:119]
	global_store_dwordx4 v[114:115], v[106:109], off nt
	global_store_dwordx4 v[114:115], v[110:113], off offset:16 nt
	v_pk_mul_f32 v[102:103], v[102:103], v[116:117] op_sel_hi:[1,0]
	v_pk_mul_f32 v[106:107], v[104:105], v[116:117] op_sel_hi:[1,0]
	v_pk_mul_f32 v[104:105], v[6:7], v[102:103]
	v_pk_mul_f32 v[102:103], v[4:5], v[106:107]
	global_store_dwordx4 v[114:115], v[102:105], off offset:512 nt
	v_pk_mul_f32 v[98:99], v[98:99], v[116:117] op_sel_hi:[1,0]
	s_nop 0
	v_pk_mul_f32 v[102:103], v[100:101], v[116:117] op_sel_hi:[1,0]
	v_pk_mul_f32 v[100:101], v[2:3], v[98:99]
	v_pk_mul_f32 v[98:99], v[0:1], v[102:103]
	global_store_dwordx4 v[114:115], v[98:101], off offset:528 nt
	s_nop 1
	v_lshl_add_u64 v[98:99], v[136:137], 0, v[184:185]
	s_waitcnt vmcnt(13)
	v_mov_b32_e32 v100, v220
	v_mov_b32_e32 v102, v221
	v_mov_b32_e32 v101, v222
	v_mov_b32_e32 v103, v223
	v_min3_f32 v104, v100, v102, v101
	v_max_f32_e32 v105, v103, v103
	v_min_f32_e32 v104, v104, v105
	v_cmp_gt_f32_e32 vcc, 0, v104
	s_cbranch_vccz .LBB0_1008
	s_branch .LBB0_1005

.LBB0_1008:
	v_pk_add_f32 v[98:99], v[100:101], v[102:103]
	v_lshlrev_b64 v[96:97], 12, v[96:97]
	v_add_f32_e32 v98, v98, v99
	ds_bpermute_b32 v99, v208, v98
	v_lshl_add_u64 v[96:97], s[8:9], 0, v[96:97]
	s_waitcnt lgkmcnt(0)
	v_add_f32_e32 v98, v98, v99
	ds_bpermute_b32 v99, v209, v98
	s_waitcnt lgkmcnt(0)
	v_add_f32_e32 v98, v98, v99
	v_fmamk_f32 v98, v98, 0x3a800000, v207
	v_mul_f32_e32 v99, 0x4b800000, v98
	v_cmp_gt_f32_e32 vcc, s49, v98
	s_nop 1
	v_cndmask_b32_e32 v98, v98, v99, vcc
	v_rsq_f32_e32 v100, v98
	v_lshl_add_u64 v[98:99], v[146:147], 2, v[96:97]
	v_mul_f32_e32 v96, 0x45800000, v100
	v_cndmask_b32_e32 v100, v100, v96, vcc
	v_pk_mul_f32 v[96:97], v[154:155], v[100:101] op_sel_hi:[1,0]
	v_pk_mul_f32 v[94:95], v[94:95], v[100:101] op_sel_hi:[1,0]
	v_pk_mul_f32 v[102:103], v[92:93], v[100:101] op_sel_hi:[1,0]
	v_pk_mul_f32 v[104:105], v[90:91], v[100:101] op_sel_hi:[1,0]
	v_pk_mul_f32 v[92:93], v[14:15], v[94:95]
	v_pk_mul_f32 v[90:91], v[12:13], v[96:97]
	v_pk_mul_f32 v[96:97], v[10:11], v[104:105]
	v_pk_mul_f32 v[94:95], v[8:9], v[102:103]
	global_store_dwordx4 v[98:99], v[90:93], off nt
	global_store_dwordx4 v[98:99], v[94:97], off offset:16 nt
	v_pk_mul_f32 v[86:87], v[86:87], v[100:101] op_sel_hi:[1,0]
	v_pk_mul_f32 v[90:91], v[88:89], v[100:101] op_sel_hi:[1,0]
	v_pk_mul_f32 v[88:89], v[6:7], v[86:87]
	v_pk_mul_f32 v[86:87], v[4:5], v[90:91]
	global_store_dwordx4 v[98:99], v[86:89], off offset:512 nt
	v_pk_mul_f32 v[82:83], v[82:83], v[100:101] op_sel_hi:[1,0]
	s_nop 0
	v_pk_mul_f32 v[86:87], v[84:85], v[100:101] op_sel_hi:[1,0]
	v_pk_mul_f32 v[84:85], v[2:3], v[82:83]
	v_pk_mul_f32 v[82:83], v[0:1], v[86:87]
	global_store_dwordx4 v[98:99], v[82:85], off offset:528 nt
	s_nop 1
	v_lshl_add_u64 v[82:83], v[136:137], 0, v[186:187]
	s_waitcnt vmcnt(16)
	v_mov_b32_e32 v84, v224
	v_mov_b32_e32 v86, v225
	v_mov_b32_e32 v85, v226
	v_mov_b32_e32 v87, v227
	v_min3_f32 v88, v84, v86, v85
	v_max_f32_e32 v89, v87, v87
	v_min_f32_e32 v88, v88, v89
	v_cmp_gt_f32_e32 vcc, 0, v88
	s_cbranch_vccz .LBB0_1014
	s_branch .LBB0_1011

.LBB0_1014:
	v_pk_add_f32 v[82:83], v[84:85], v[86:87]
	v_lshlrev_b64 v[80:81], 12, v[80:81]
	v_add_f32_e32 v82, v82, v83
	ds_bpermute_b32 v83, v208, v82
	v_lshl_add_u64 v[80:81], s[8:9], 0, v[80:81]
	s_waitcnt lgkmcnt(0)
	v_add_f32_e32 v82, v82, v83
	ds_bpermute_b32 v83, v209, v82
	s_waitcnt lgkmcnt(0)
	v_add_f32_e32 v82, v82, v83
	v_fmamk_f32 v82, v82, 0x3a800000, v207
	v_mul_f32_e32 v83, 0x4b800000, v82
	v_cmp_gt_f32_e32 vcc, s49, v82
	s_nop 1
	v_cndmask_b32_e32 v82, v82, v83, vcc
	v_rsq_f32_e32 v84, v82
	v_lshl_add_u64 v[82:83], v[146:147], 2, v[80:81]
	v_mul_f32_e32 v80, 0x45800000, v84
	v_cndmask_b32_e32 v84, v84, v80, vcc
	v_pk_mul_f32 v[80:81], v[156:157], v[84:85] op_sel_hi:[1,0]
	v_pk_mul_f32 v[78:79], v[78:79], v[84:85] op_sel_hi:[1,0]
	v_pk_mul_f32 v[86:87], v[76:77], v[84:85] op_sel_hi:[1,0]
	v_pk_mul_f32 v[88:89], v[74:75], v[84:85] op_sel_hi:[1,0]
	v_pk_mul_f32 v[76:77], v[14:15], v[78:79]
	v_pk_mul_f32 v[74:75], v[12:13], v[80:81]
	v_pk_mul_f32 v[80:81], v[10:11], v[88:89]
	v_pk_mul_f32 v[78:79], v[8:9], v[86:87]
	global_store_dwordx4 v[82:83], v[74:77], off nt
	global_store_dwordx4 v[82:83], v[78:81], off offset:16 nt
	v_pk_mul_f32 v[70:71], v[70:71], v[84:85] op_sel_hi:[1,0]
	v_pk_mul_f32 v[74:75], v[72:73], v[84:85] op_sel_hi:[1,0]
	v_pk_mul_f32 v[72:73], v[6:7], v[70:71]
	v_pk_mul_f32 v[70:71], v[4:5], v[74:75]
	global_store_dwordx4 v[82:83], v[70:73], off offset:512 nt
	v_pk_mul_f32 v[66:67], v[66:67], v[84:85] op_sel_hi:[1,0]
	s_nop 0
	v_pk_mul_f32 v[70:71], v[68:69], v[84:85] op_sel_hi:[1,0]
	v_pk_mul_f32 v[68:69], v[2:3], v[66:67]
	v_pk_mul_f32 v[66:67], v[0:1], v[70:71]
	global_store_dwordx4 v[82:83], v[66:69], off offset:528 nt
	s_nop 1
	v_lshl_add_u64 v[66:67], v[136:137], 0, v[188:189]
	s_waitcnt vmcnt(19)
	v_mov_b32_e32 v68, v228
	v_mov_b32_e32 v70, v229
	v_mov_b32_e32 v69, v230
	v_mov_b32_e32 v71, v231
	v_min3_f32 v72, v68, v70, v69
	v_max_f32_e32 v73, v71, v71
	v_min_f32_e32 v72, v72, v73
	v_cmp_gt_f32_e32 vcc, 0, v72
	s_cbranch_vccz .LBB0_1020
	s_branch .LBB0_1017

.LBB0_1020:
	v_pk_add_f32 v[66:67], v[68:69], v[70:71]
	v_lshlrev_b64 v[64:65], 12, v[64:65]
	v_add_f32_e32 v66, v66, v67
	ds_bpermute_b32 v67, v208, v66
	v_lshl_add_u64 v[64:65], s[8:9], 0, v[64:65]
	s_waitcnt lgkmcnt(0)
	v_add_f32_e32 v66, v66, v67
	ds_bpermute_b32 v67, v209, v66
	s_waitcnt lgkmcnt(0)
	v_add_f32_e32 v66, v66, v67
	v_fmamk_f32 v66, v66, 0x3a800000, v207
	v_mul_f32_e32 v67, 0x4b800000, v66
	v_cmp_gt_f32_e32 vcc, s49, v66
	s_nop 1
	v_cndmask_b32_e32 v66, v66, v67, vcc
	v_rsq_f32_e32 v68, v66
	v_lshl_add_u64 v[66:67], v[146:147], 2, v[64:65]
	v_mul_f32_e32 v64, 0x45800000, v68
	v_cndmask_b32_e32 v68, v68, v64, vcc
	v_pk_mul_f32 v[64:65], v[158:159], v[68:69] op_sel_hi:[1,0]
	v_pk_mul_f32 v[62:63], v[62:63], v[68:69] op_sel_hi:[1,0]
	v_pk_mul_f32 v[70:71], v[60:61], v[68:69] op_sel_hi:[1,0]
	v_pk_mul_f32 v[72:73], v[58:59], v[68:69] op_sel_hi:[1,0]
	v_pk_mul_f32 v[60:61], v[14:15], v[62:63]
	v_pk_mul_f32 v[58:59], v[12:13], v[64:65]
	v_pk_mul_f32 v[64:65], v[10:11], v[72:73]
	v_pk_mul_f32 v[62:63], v[8:9], v[70:71]
	global_store_dwordx4 v[66:67], v[58:61], off nt
	global_store_dwordx4 v[66:67], v[62:65], off offset:16 nt
	v_pk_mul_f32 v[54:55], v[54:55], v[68:69] op_sel_hi:[1,0]
	v_pk_mul_f32 v[58:59], v[56:57], v[68:69] op_sel_hi:[1,0]
	v_pk_mul_f32 v[56:57], v[6:7], v[54:55]
	v_pk_mul_f32 v[54:55], v[4:5], v[58:59]
	global_store_dwordx4 v[66:67], v[54:57], off offset:512 nt
	v_pk_mul_f32 v[50:51], v[50:51], v[68:69] op_sel_hi:[1,0]
	s_nop 0
	v_pk_mul_f32 v[54:55], v[52:53], v[68:69] op_sel_hi:[1,0]
	v_pk_mul_f32 v[52:53], v[2:3], v[50:51]
	v_pk_mul_f32 v[50:51], v[0:1], v[54:55]
	global_store_dwordx4 v[66:67], v[50:53], off offset:528 nt
	s_nop 1
	v_lshl_add_u64 v[50:51], v[136:137], 0, v[190:191]
	s_waitcnt vmcnt(22)
	v_mov_b32_e32 v52, v232
	v_mov_b32_e32 v54, v233
	v_mov_b32_e32 v53, v234
	v_mov_b32_e32 v55, v235
	v_min3_f32 v56, v52, v54, v53
	v_max_f32_e32 v57, v55, v55
	v_min_f32_e32 v56, v56, v57
	v_cmp_gt_f32_e32 vcc, 0, v56
	s_cbranch_vccz .LBB0_1026
	s_branch .LBB0_1023

.LBB0_1026:
	v_pk_add_f32 v[50:51], v[52:53], v[54:55]
	v_lshlrev_b64 v[48:49], 12, v[48:49]
	v_add_f32_e32 v50, v50, v51
	ds_bpermute_b32 v51, v208, v50
	v_lshl_add_u64 v[48:49], s[8:9], 0, v[48:49]
	s_waitcnt lgkmcnt(0)
	v_add_f32_e32 v50, v50, v51
	ds_bpermute_b32 v51, v209, v50
	s_waitcnt lgkmcnt(0)
	v_add_f32_e32 v50, v50, v51
	v_fmamk_f32 v50, v50, 0x3a800000, v207
	v_mul_f32_e32 v51, 0x4b800000, v50
	v_cmp_gt_f32_e32 vcc, s49, v50
	s_nop 1
	v_cndmask_b32_e32 v50, v50, v51, vcc
	v_rsq_f32_e32 v52, v50
	v_lshl_add_u64 v[50:51], v[146:147], 2, v[48:49]
	v_mul_f32_e32 v48, 0x45800000, v52
	v_cndmask_b32_e32 v52, v52, v48, vcc
	v_pk_mul_f32 v[48:49], v[160:161], v[52:53] op_sel_hi:[1,0]
	v_pk_mul_f32 v[46:47], v[46:47], v[52:53] op_sel_hi:[1,0]
	v_pk_mul_f32 v[54:55], v[44:45], v[52:53] op_sel_hi:[1,0]
	v_pk_mul_f32 v[56:57], v[42:43], v[52:53] op_sel_hi:[1,0]
	v_pk_mul_f32 v[44:45], v[14:15], v[46:47]
	v_pk_mul_f32 v[42:43], v[12:13], v[48:49]
	v_pk_mul_f32 v[48:49], v[10:11], v[56:57]
	v_pk_mul_f32 v[46:47], v[8:9], v[54:55]
	global_store_dwordx4 v[50:51], v[42:45], off nt
	global_store_dwordx4 v[50:51], v[46:49], off offset:16 nt
	v_pk_mul_f32 v[38:39], v[38:39], v[52:53] op_sel_hi:[1,0]
	v_pk_mul_f32 v[42:43], v[40:41], v[52:53] op_sel_hi:[1,0]
	v_pk_mul_f32 v[40:41], v[6:7], v[38:39]
	v_pk_mul_f32 v[38:39], v[4:5], v[42:43]
	global_store_dwordx4 v[50:51], v[38:41], off offset:512 nt
	v_pk_mul_f32 v[34:35], v[34:35], v[52:53] op_sel_hi:[1,0]
	s_nop 0
	v_pk_mul_f32 v[38:39], v[36:37], v[52:53] op_sel_hi:[1,0]
	v_pk_mul_f32 v[36:37], v[2:3], v[34:35]
	v_pk_mul_f32 v[34:35], v[0:1], v[38:39]
	global_store_dwordx4 v[50:51], v[34:37], off offset:528 nt
	s_nop 1
	v_lshl_add_u64 v[34:35], v[136:137], 0, v[192:193]
	s_waitcnt vmcnt(25)
	v_mov_b32_e32 v36, v236
	v_mov_b32_e32 v38, v237
	v_mov_b32_e32 v37, v238
	v_mov_b32_e32 v39, v239
	v_min3_f32 v40, v36, v38, v37
	v_max_f32_e32 v41, v39, v39
	v_min_f32_e32 v40, v40, v41
	v_cmp_gt_f32_e32 vcc, 0, v40
	s_cbranch_vccz .LBB0_1032
	s_branch .LBB0_1029

.LBB0_1032:
	v_pk_add_f32 v[34:35], v[36:37], v[38:39]
	v_lshlrev_b64 v[32:33], 12, v[32:33]
	v_add_f32_e32 v34, v34, v35
	ds_bpermute_b32 v35, v208, v34
	v_lshl_add_u64 v[32:33], s[8:9], 0, v[32:33]
	v_lshl_add_u64 v[40:41], v[146:147], 2, v[32:33]
	s_waitcnt lgkmcnt(0)
	v_add_f32_e32 v34, v34, v35
	ds_bpermute_b32 v35, v209, v34
	s_waitcnt lgkmcnt(0)
	v_add_f32_e32 v34, v34, v35
	v_fmamk_f32 v34, v34, 0x3a800000, v207
	v_mul_f32_e32 v35, 0x4b800000, v34
	v_cmp_gt_f32_e32 vcc, s49, v34
	s_nop 1
	v_cndmask_b32_e32 v34, v34, v35, vcc
	v_rsq_f32_e32 v34, v34
	s_nop 0
	v_mul_f32_e32 v32, 0x45800000, v34
	v_cndmask_b32_e32 v42, v34, v32, vcc
	v_pk_mul_f32 v[28:29], v[28:29], v[42:43] op_sel_hi:[1,0]
	v_pk_mul_f32 v[32:33], v[172:173], v[42:43] op_sel_hi:[1,0]
	v_pk_mul_f32 v[34:35], v[168:169], v[42:43] op_sel_hi:[1,0]
	v_pk_mul_f32 v[38:39], v[10:11], v[28:29]
	v_pk_mul_f32 v[28:29], v[24:25], v[42:43] op_sel_hi:[1,0]
	v_pk_mul_f32 v[22:23], v[22:23], v[42:43] op_sel_hi:[1,0]
	v_pk_mul_f32 v[36:37], v[164:165], v[42:43] op_sel_hi:[1,0]
	v_pk_mul_f32 v[34:35], v[14:15], v[34:35]
	v_pk_mul_f32 v[32:33], v[12:13], v[32:33]
	v_pk_mul_f32 v[24:25], v[6:7], v[22:23]
	v_pk_mul_f32 v[22:23], v[4:5], v[28:29]
	v_pk_mul_f32 v[36:37], v[8:9], v[36:37]
	global_store_dwordx4 v[40:41], v[32:35], off nt
	global_store_dwordx4 v[40:41], v[36:39], off offset:16 nt
	global_store_dwordx4 v[40:41], v[22:25], off offset:512 nt
	v_pk_mul_f32 v[18:19], v[18:19], v[42:43] op_sel_hi:[1,0]
	s_nop 0
	v_pk_mul_f32 v[22:23], v[20:21], v[42:43] op_sel_hi:[1,0]
	v_pk_mul_f32 v[20:21], v[2:3], v[18:19]
	v_pk_mul_f32 v[18:19], v[0:1], v[22:23]
	v_lshl_add_u64 v[22:23], v[136:137], 0, v[194:195]
	global_store_dwordx4 v[40:41], v[18:21], off offset:528 nt
	s_waitcnt vmcnt(28)
	v_mov_b32_e32 v18, v244
	v_mov_b32_e32 v20, v245
	v_mov_b32_e32 v19, v246
	v_mov_b32_e32 v21, v247
	v_min3_f32 v24, v18, v20, v19
	v_max_f32_e32 v25, v21, v21
	v_min_f32_e32 v24, v24, v25
	v_cmp_gt_f32_e32 vcc, 0, v24
	s_cbranch_vccz .LBB0_965
	s_branch .LBB0_1035
